# ph13: blocks 0..63 run their NA cache-conversion tile first (overlaps co-resident GEMM) instead of as a phase tail
# speedup vs baseline: 1.0189x; 1.0021x over previous
.LBB0_1262:
	s_cmp_gt_i32 s22, 13
	s_cselect_b64 s[4:5], -1, 0
	s_cmp_lt_i32 s23, 14
	s_cselect_b64 s[6:7], -1, 0
	s_or_b64 s[4:5], s[4:5], s[6:7]
	s_and_b64 vcc, exec, s[4:5]
	s_cbranch_vccnz .LBB0_1754
	s_cmpk_gt_i32 s2, 0x83f
	s_cbranch_scc1 .LBB0_1701
	s_load_dwordx2 s[4:5], s[0:1], 0x80
	s_load_dwordx2 s[24:25], s[0:1], 0x170
	s_load_dwordx4 s[8:11], s[0:1], 0x160
	s_waitcnt vmcnt(0)
	v_bfe_u32 v2, v0, 7, 3
	v_and_b32_e32 v4, 31, v0
	v_mul_u32_u24_e32 v119, 0x60, v2
	v_and_b32_e32 v3, 0x3ff, v0
	v_or_b32_e32 v2, v119, v4
	s_waitcnt lgkmcnt(0)
	s_add_u32 s26, s4, 0x3500000
	v_bfe_u32 v6, v3, 6, 1
	v_bfe_u32 v8, v0, 5, 1
	v_lshrrev_b32_e32 v9, 1, v0
	v_lshlrev_b32_e32 v120, 7, v2
	v_lshlrev_b32_e32 v2, 7, v4
	s_addc_u32 s27, s5, 0
	v_bfe_u32 v10, v0, 1, 3
	v_lshl_or_b32 v121, v6, 13, v2
	v_bitop3_b32 v2, v8, v9, 7 bitop3:0x78
	s_add_u32 s28, s4, 0x4500000
	v_lshlrev_b32_e32 v123, 4, v2
	v_bitop3_b32 v2, v8, v10, 2 bitop3:0x36
	s_movk_i32 s4, 0x2200
	v_mul_u32_u24_e32 v4, 0x110, v4
	s_addc_u32 s29, s5, 0
	v_lshlrev_b32_e32 v124, 4, v2
	v_bitop3_b32 v2, v8, v10, 4 bitop3:0x36
	v_mad_u32_u24 v4, v1, s4, v4
	s_load_dwordx4 s[16:19], s[0:1], 0x90
	s_load_dwordx2 s[4:5], s[0:1], 0xf8
	s_movk_i32 s3, 0x3ff
	s_load_dwordx4 s[12:15], s[0:1], 0x20
	v_lshlrev_b32_e32 v98, 2, v3
	v_bfe_u32 v5, v0, 4, 6
	v_lshlrev_b32_e32 v125, 4, v2
	v_bitop3_b32 v2, v8, v10, 6 bitop3:0x36
	v_bitop3_b32 v5, v5, v0, s3 bitop3:0x78
	v_and_b32_e32 v7, 63, v0
	v_lshlrev_b32_e32 v126, 4, v2
	v_mul_u32_u24_e32 v2, 0x2200, v1
	v_and_b32_e32 v131, 60, v98
	s_add_u32 s30, s0, 0x468
	v_mov_b32_e32 v101, 0
	v_or_b32_e32 v128, 0xfffff800, v7
	v_lshl_or_b32 v129, v7, 2, v2
	v_bfe_u32 v130, v0, 4, 2
	v_lshl_or_b32 v7, v131, 2, v2
	s_addc_u32 s31, s1, 0
	v_mul_u32_u24_e32 v2, 0x2400, v3
	v_lshlrev_b32_e32 v100, 3, v3
	v_lshlrev_b32_e32 v3, 4, v5
	v_lshlrev_b32_e32 v117, 10, v1
	v_lshlrev_b32_e32 v127, 6, v6
	v_lshlrev_b32_e32 v6, 4, v8
	v_mul_u32_u24_e32 v8, 0x110, v130
	v_lshl_add_u64 v[102:103], s[10:11], 0, v[100:101]
	s_add_u32 s45, s24, 0x800000
	v_and_b32_e32 v100, 0x70, v3
	v_mov_b32_e32 v99, v101
	v_bfe_u32 v116, v0, 3, 7
	v_or_b32_e32 v118, 0xc000, v117
	v_or_b32_e32 v122, 0xc000, v121
	v_or_b32_e32 v132, 4, v130
	v_or_b32_e32 v133, 8, v130
	v_or_b32_e32 v134, 12, v130
	v_or_b32_e32 v135, 16, v130
	v_or_b32_e32 v136, 20, v130
	v_or_b32_e32 v137, 24, v130
	v_or_b32_e32 v138, 28, v130
	s_addc_u32 s56, s25, 0
	s_waitcnt lgkmcnt(0)
	v_lshl_add_u64 v[104:105], s[16:17], 0, v[100:101]
	v_lshl_add_u64 v[106:107], s[4:5], 0, v[100:101]
	s_movk_i32 s57, 0x1000
	s_mov_b32 s17, 0
	v_lshlrev_b32_e32 v108, 1, v2
	s_movk_i32 s58, 0x2000
	s_mov_b64 s[34:35], 0x10000
	s_mov_b64 s[36:37], 0x20000
	s_mov_b64 s[38:39], 0x30000
	s_mov_b64 s[40:41], 0x40000
	s_mov_b64 s[42:43], 0x50000
	s_mov_b32 s59, 0x240000
	s_movk_i32 s60, 0xfff
	s_movk_i32 s61, 0x1100
	s_mov_b32 s44, 0x3e38aa3b
	s_movk_i32 s62, 0xfe0
	s_movk_i32 s63, 0xfc0
	v_lshlrev_b32_e32 v139, 2, v98
	v_add_u32_e32 v140, v4, v6
	v_mov_b64_e32 v[110:111], 0x400000
	v_mov_b32_e32 v141, 0x440
	v_mov_b32_e32 v142, 0x550
	v_mov_b32_e32 v143, 0x660
	v_mov_b32_e32 v144, 0x770
	v_mov_b32_e32 v145, 0x900
	v_mov_b32_e32 v147, 0x100
	v_add_u32_e32 v149, v7, v8
	s_mov_b32 s64, s2
	s_mov_b32 s96, 0
	s_movk_i32 s97, 0x840
	s_load_dword s4, s[30:31], 0x0
	s_waitcnt lgkmcnt(0)
	s_cmpk_lg_u32 s4, 0x200
	s_cbranch_scc1 .Lna13_order_done
	s_cmpk_gt_u32 s2, 0x3f
	s_cbranch_scc1 .Lna13_order_done
	s_add_i32 s64, s2, 0x800
	s_mov_b32 s96, 1
	s_movk_i32 s97, 0x800
.Lna13_order_done:
	s_branch .LBB0_1267
.LBB0_1265:
	s_or_b64 exec, exec, s[50:51]
	s_waitcnt lgkmcnt(0)
.LBB0_1266:
	s_load_dword s4, s[30:31], 0x0
	s_waitcnt lgkmcnt(0)
	s_add_i32 s64, s4, s64
	s_cmp_eq_u32 s96, 1
	s_cbranch_scc0 .Lna13_latch
	s_mov_b32 s96, 2
	s_mov_b32 s64, s2
.Lna13_latch:
	s_cmp_lt_i32 s64, s97
	s_cbranch_scc0 .LBB0_1701
